# first-iteration peel (relaxed vmcnt over previous unit's stores) extended to RES, AIN and KVQ GEMM loops
# speedup vs baseline: 1.0046x; 1.0046x over previous
.LBB0_253:
	v_lshrrev_b32_e32 v17, 1, v130
	s_add_u32 s56, s82, 0xa200000
	v_and_b32_e32 v17, 24, v17
	s_addc_u32 s37, s83, 0
	v_and_b32_e32 v16, 15, v130
	v_lshlrev_b32_e32 v18, 1, v17
	s_lshl_b32 s21, s21, 5
	v_lshl_or_b32 v131, s7, 6, v16
	v_lshl_or_b32 v18, v16, 6, v18
	v_lshlrev_b32_e32 v16, 2, v16
	s_and_b32 s30, s21, 0x60
	s_add_i32 m0, s27, 0x18000
	v_lshl_add_u64 v[8:9], v[8:9], 0, s[66:67]
	s_lshl_b32 s22, s7, 13
	v_and_b32_e32 v19, 32, v16
	s_lshl_b32 s21, s30, 7
	s_waitcnt vmcnt(2)
	s_barrier
	global_load_lds_dwordx4 v[8:9], off
	v_lshl_add_u64 v[6:7], v[6:7], 0, s[66:67]
	s_add_i32 m0, s27, 0x1a000
	s_add_i32 s24, s27, 0x8000
	s_add_i32 s25, s27, 0xa000
	v_bitop3_b32 v20, v18, s22, v19 bitop3:0xde
	global_load_lds_dwordx4 v[6:7], off
	v_lshl_add_u64 v[2:3], v[2:3], 0, s[66:67]
	s_mov_b32 m0, s24
	s_add_u32 s22, s50, 0x40080
	global_load_lds_dwordx4 v[2:3], off
	v_lshl_add_u64 v[2:3], v[4:5], 0, s[66:67]
	s_mov_b32 m0, s25
	s_addc_u32 s23, s51, 0
	global_load_lds_dwordx4 v[2:3], off
	s_add_i32 m0, s27, 0x1c000
	v_lshl_add_u64 v[2:3], s[22:23], 0, v[146:147]
	global_load_lds_dwordx4 v[2:3], off
	v_lshl_add_u64 v[2:3], s[22:23], 0, v[132:133]
	s_add_i32 m0, s27, 0x1e000
	v_and_b32_e32 v4, 1, v14
	global_load_lds_dwordx4 v[2:3], off
	v_lshlrev_b32_e32 v3, 14, v14
	v_and_b32_e32 v3, 0xffff8000, v3
	v_lshl_add_u32 v3, v13, 11, v3
	v_lshl_or_b32 v3, v4, 6, v3
	s_cmpk_lt_u32 s6, 0x100
	v_lshl_add_u32 v150, v15, 1, v3
	v_lshlrev_b32_e32 v3, 14, v10
	s_cselect_b64 s[44:45], -1, 0
	s_lshl_b32 s6, s7, 8
	v_and_b32_e32 v3, 0xffff8000, v3
	s_waitcnt vmcnt(6)
	s_add_i32 s6, s6, 0
	v_lshl_add_u32 v3, v11, 11, v3
	v_and_b32_e32 v4, 1, v10
	v_bitop3_b32 v159, s21, v18, v19 bitop3:0xf6
	v_cndmask_b32_e64 v18, 0, 1, s[92:93]
	v_or_b32_e32 v2, s30, v17
	s_add_i32 s6, s6, 0x20400
	v_lshl_or_b32 v3, v4, 6, v3
	v_readfirstlane_b32 s21, v18
	v_add_u32_e32 v160, s6, v16
	v_mov_b32_e32 v151, v135
	v_lshl_add_u32 v152, v12, 1, v3
	v_mov_b32_e32 v153, v135
	s_mov_b32 s69, 0
	v_add_u32_e32 v161, 0, v20
	v_lshlrev_b32_e32 v134, 1, v2
	s_mov_b32 s30, 0
	s_barrier
	v_writelane_b32 v253, 0, 0
	s_branch .LBB0_256

.LBB0_255:
	v_writelane_b32 v253, 1, 0
	s_andn2_b64 vcc, exec, s[6:7]
	s_mov_b32 s69, s68
	s_mov_b32 s96, s46
	s_mov_b32 s26, s92
	s_mov_b64 s[50:51], s[94:95]
	s_mov_b64 s[98:99], s[22:23]
	s_cbranch_vccz .LBB0_265

.LBB0_258:
	s_ashr_i32 s93, s92, 31
	s_lshl_b64 s[22:23], s[92:93], 19
	s_add_u32 s22, s78, s22
	s_addc_u32 s23, s79, s23
	s_and_b64 s[52:53], s[6:7], exec
	s_cselect_b32 s60, s23, s99
	s_cselect_b32 s93, s22, s98
	s_ashr_i32 s47, s46, 31
	s_lshl_b64 s[52:53], s[46:47], 19
	s_add_u32 s94, s19, s52
	s_addc_u32 s95, s62, s53
	s_and_b64 s[52:53], s[6:7], exec
	s_cselect_b32 s47, s95, s51
	s_cselect_b32 vcc_lo, s94, s50
	s_add_u32 s98, s98, 0x40080
	s_addc_u32 s99, s99, 0
	s_add_u32 vcc_hi, s50, 0x100
	v_mov_b32_e32 v2, 0
	s_addc_u32 s70, s51, 0
	s_mov_b32 s71, -2
	v_mov_b32_e32 v3, v2
	v_mov_b32_e32 v4, v2
	v_mov_b32_e32 v5, v2
	v_mov_b32_e32 v6, v2
	v_mov_b32_e32 v7, v2
	v_mov_b32_e32 v8, v2
	v_mov_b32_e32 v9, v2
	v_mov_b32_e32 v14, v2
	v_mov_b32_e32 v15, v2
	v_mov_b32_e32 v16, v2
	v_mov_b32_e32 v17, v2
	v_mov_b32_e32 v22, v2
	v_mov_b32_e32 v23, v2
	v_mov_b32_e32 v24, v2
	v_mov_b32_e32 v25, v2
	v_mov_b32_e32 v30, v2
	v_mov_b32_e32 v31, v2
	v_mov_b32_e32 v32, v2
	v_mov_b32_e32 v33, v2
	v_mov_b32_e32 v38, v2
	v_mov_b32_e32 v39, v2
	v_mov_b32_e32 v40, v2
	v_mov_b32_e32 v41, v2
	v_mov_b32_e32 v46, v2
	v_mov_b32_e32 v47, v2
	v_mov_b32_e32 v48, v2
	v_mov_b32_e32 v49, v2
	v_mov_b32_e32 v54, v2
	v_mov_b32_e32 v55, v2
	v_mov_b32_e32 v56, v2
	v_mov_b32_e32 v57, v2
	v_mov_b32_e32 v10, v2
	v_mov_b32_e32 v11, v2
	v_mov_b32_e32 v12, v2
	v_mov_b32_e32 v13, v2
	v_mov_b32_e32 v18, v2
	v_mov_b32_e32 v19, v2
	v_mov_b32_e32 v20, v2
	v_mov_b32_e32 v21, v2
	v_mov_b32_e32 v26, v2
	v_mov_b32_e32 v27, v2
	v_mov_b32_e32 v28, v2
	v_mov_b32_e32 v29, v2
	v_mov_b32_e32 v34, v2
	v_mov_b32_e32 v35, v2
	v_mov_b32_e32 v36, v2
	v_mov_b32_e32 v37, v2
	v_mov_b32_e32 v42, v2
	v_mov_b32_e32 v43, v2
	v_mov_b32_e32 v44, v2
	v_mov_b32_e32 v45, v2
	v_mov_b32_e32 v50, v2
	v_mov_b32_e32 v51, v2
	v_mov_b32_e32 v52, v2
	v_mov_b32_e32 v53, v2
	v_mov_b32_e32 v58, v2
	v_mov_b32_e32 v59, v2
	v_mov_b32_e32 v60, v2
	v_mov_b32_e32 v61, v2
	v_mov_b32_e32 v62, v2
	v_mov_b32_e32 v63, v2
	v_mov_b32_e32 v64, v2
	v_mov_b32_e32 v65, v2
	v_mov_b32_e32 v66, v2
	v_mov_b32_e32 v67, v2
	v_mov_b32_e32 v68, v2
	v_mov_b32_e32 v69, v2
	v_mov_b32_e32 v70, v2
	v_mov_b32_e32 v71, v2
	v_mov_b32_e32 v72, v2
	v_mov_b32_e32 v73, v2
	v_mov_b32_e32 v78, v2
	v_mov_b32_e32 v79, v2
	v_mov_b32_e32 v80, v2
	v_mov_b32_e32 v81, v2
	v_mov_b32_e32 v86, v2
	v_mov_b32_e32 v87, v2
	v_mov_b32_e32 v88, v2
	v_mov_b32_e32 v89, v2
	v_mov_b32_e32 v94, v2
	v_mov_b32_e32 v95, v2
	v_mov_b32_e32 v96, v2
	v_mov_b32_e32 v97, v2
	v_mov_b32_e32 v102, v2
	v_mov_b32_e32 v103, v2
	v_mov_b32_e32 v104, v2
	v_mov_b32_e32 v105, v2
	v_mov_b32_e32 v110, v2
	v_mov_b32_e32 v111, v2
	v_mov_b32_e32 v112, v2
	v_mov_b32_e32 v113, v2
	v_mov_b32_e32 v118, v2
	v_mov_b32_e32 v119, v2
	v_mov_b32_e32 v120, v2
	v_mov_b32_e32 v121, v2
	v_mov_b32_e32 v74, v2
	v_mov_b32_e32 v75, v2
	v_mov_b32_e32 v76, v2
	v_mov_b32_e32 v77, v2
	v_mov_b32_e32 v82, v2
	v_mov_b32_e32 v83, v2
	v_mov_b32_e32 v84, v2
	v_mov_b32_e32 v85, v2
	v_mov_b32_e32 v90, v2
	v_mov_b32_e32 v91, v2
	v_mov_b32_e32 v92, v2
	v_mov_b32_e32 v93, v2
	v_mov_b32_e32 v98, v2
	v_mov_b32_e32 v99, v2
	v_mov_b32_e32 v100, v2
	v_mov_b32_e32 v101, v2
	v_mov_b32_e32 v106, v2
	v_mov_b32_e32 v107, v2
	v_mov_b32_e32 v108, v2
	v_mov_b32_e32 v109, v2
	v_mov_b32_e32 v114, v2
	v_mov_b32_e32 v115, v2
	v_mov_b32_e32 v116, v2
	v_mov_b32_e32 v117, v2
	v_mov_b32_e32 v122, v2
	v_mov_b32_e32 v123, v2
	v_mov_b32_e32 v124, v2
	v_mov_b32_e32 v125, v2
	v_mov_b32_e32 v126, v2
	v_mov_b32_e32 v127, v2
	v_mov_b32_e32 v128, v2
	v_mov_b32_e32 v129, v2
	v_readlane_b32 s50, v253, 0
	s_nop 1
	s_cmp_eq_u32 s50, 0
	s_cbranch_scc1 .LBB0_259
	s_add_u32 s50, s98, 0xfffc0080
	s_addc_u32 s51, s99, -1
	s_add_i32 s72, 0, 0x10000
	s_cmp_eq_u32 s71, 12
	s_cselect_b32 s53, s60, s51
	s_cselect_b32 s52, s93, s50
	v_add_u32_e32 v162, s72, v159
	s_cselect_b32 s51, s47, s70
	s_cselect_b32 s50, vcc_lo, vcc_hi
	s_add_i32 s41, 0, 0x14000
	ds_read_b128 v[154:157], v162
	ds_read_b128 v[178:181], v162 offset:1024
	ds_read_b128 v[182:185], v162 offset:2048
	ds_read_b128 v[186:189], v162 offset:3072
	v_add_u32_e32 v162, s41, v159
	ds_read_b128 v[190:193], v162
	ds_read_b128 v[194:197], v162 offset:1024
	ds_read_b128 v[198:201], v162 offset:2048
	ds_read_b128 v[202:205], v162 offset:3072
	v_lshl_add_u64 v[164:165], s[98:99], 0, v[150:151]
	s_add_i32 m0, s27, 0xc000
	ds_read_b128 v[206:209], v161
	ds_read_b128 v[210:213], v161 offset:1024
	ds_read_b128 v[214:217], v161 offset:2048
	ds_read_b128 v[218:221], v161 offset:3072
	ds_read_b128 v[222:225], v161 offset:4096
	ds_read_b128 v[226:229], v161 offset:5120
	ds_read_b128 v[230:233], v161 offset:6144
	ds_read_b128 v[234:237], v161 offset:7168
	global_load_lds_dwordx4 v[164:165], off
	v_lshl_add_u64 v[164:165], s[98:99], 0, v[152:153]
	s_add_i32 m0, s27, 0xe000
	s_nop 0
	global_load_lds_dwordx4 v[164:165], off
	s_waitcnt vmcnt(24)
	s_waitcnt lgkmcnt(0)
	s_barrier
	s_setprio 1
	s_waitcnt lgkmcnt(0)
	v_mfma_f32_16x16x32_bf16 v[126:129], v[154:157], v[206:209], v[126:129]
	v_mfma_f32_16x16x32_bf16 v[122:125], v[182:185], v[206:209], v[122:125]
	v_mfma_f32_16x16x32_bf16 v[114:117], v[154:157], v[214:217], v[114:117]
	v_mfma_f32_16x16x32_bf16 v[106:109], v[182:185], v[214:217], v[106:109]
	v_mfma_f32_16x16x32_bf16 v[98:101], v[154:157], v[222:225], v[98:101]
	v_mfma_f32_16x16x32_bf16 v[90:93], v[182:185], v[222:225], v[90:93]
	v_mfma_f32_16x16x32_bf16 v[82:85], v[154:157], v[230:233], v[82:85]
	v_mfma_f32_16x16x32_bf16 v[74:77], v[182:185], v[230:233], v[74:77]
	v_mfma_f32_16x16x32_bf16 v[126:129], v[178:181], v[210:213], v[126:129]
	v_mfma_f32_16x16x32_bf16 v[122:125], v[186:189], v[210:213], v[122:125]
	v_mfma_f32_16x16x32_bf16 v[114:117], v[178:181], v[218:221], v[114:117]
	v_mfma_f32_16x16x32_bf16 v[106:109], v[186:189], v[218:221], v[106:109]
	v_mfma_f32_16x16x32_bf16 v[98:101], v[178:181], v[226:229], v[98:101]
	v_mfma_f32_16x16x32_bf16 v[90:93], v[186:189], v[226:229], v[90:93]
	v_mfma_f32_16x16x32_bf16 v[82:85], v[178:181], v[234:237], v[82:85]
	v_mfma_f32_16x16x32_bf16 v[74:77], v[186:189], v[234:237], v[74:77]
	s_setprio 0
	s_setprio 1
	v_mfma_f32_16x16x32_bf16 v[118:121], v[190:193], v[206:209], v[118:121]
	v_mfma_f32_16x16x32_bf16 v[110:113], v[198:201], v[206:209], v[110:113]
	v_mfma_f32_16x16x32_bf16 v[102:105], v[190:193], v[214:217], v[102:105]
	v_mfma_f32_16x16x32_bf16 v[94:97], v[198:201], v[214:217], v[94:97]
	v_mfma_f32_16x16x32_bf16 v[86:89], v[190:193], v[222:225], v[86:89]
	v_mfma_f32_16x16x32_bf16 v[78:81], v[198:201], v[222:225], v[78:81]
	v_mfma_f32_16x16x32_bf16 v[70:73], v[190:193], v[230:233], v[70:73]
	v_mfma_f32_16x16x32_bf16 v[66:69], v[198:201], v[230:233], v[66:69]
	v_mfma_f32_16x16x32_bf16 v[118:121], v[194:197], v[210:213], v[118:121]
	v_mfma_f32_16x16x32_bf16 v[110:113], v[202:205], v[210:213], v[110:113]
	v_mfma_f32_16x16x32_bf16 v[102:105], v[194:197], v[218:221], v[102:105]
	v_mfma_f32_16x16x32_bf16 v[94:97], v[202:205], v[218:221], v[94:97]
	s_setprio 2
	s_barrier
	v_mfma_f32_16x16x32_bf16 v[86:89], v[194:197], v[226:229], v[86:89]
	v_mfma_f32_16x16x32_bf16 v[78:81], v[202:205], v[226:229], v[78:81]
	v_mfma_f32_16x16x32_bf16 v[70:73], v[194:197], v[234:237], v[70:73]
	v_mfma_f32_16x16x32_bf16 v[66:69], v[202:205], v[234:237], v[66:69]
	s_setprio 0
	s_add_i32 s72, s72, s65
	v_lshl_add_u64 v[164:165], s[50:51], 0, v[146:147]
	s_mov_b32 m0, s72
	ds_read_b128 v[206:209], v161 offset:16384
	ds_read_b128 v[210:213], v161 offset:17408
	ds_read_b128 v[214:217], v161 offset:18432
	ds_read_b128 v[218:221], v161 offset:19456
	ds_read_b128 v[222:225], v161 offset:20480
	ds_read_b128 v[226:229], v161 offset:21504
	ds_read_b128 v[230:233], v161 offset:22528
	ds_read_b128 v[234:237], v161 offset:23552
	global_load_lds_dwordx4 v[164:165], off
	s_add_i32 m0, s72, 0x2000
	s_add_u32 s72, s50, 0x40000
	v_lshl_add_u64 v[238:239], s[50:51], 0, v[132:133]
	s_addc_u32 s73, s51, 0
	s_add_i32 s41, s41, s65
	global_load_lds_dwordx4 v[238:239], off
	v_lshl_add_u64 v[240:241], s[72:73], 0, v[146:147]
	s_mov_b32 m0, s41
	v_lshl_add_u64 v[242:243], s[52:53], 0, v[144:145]
	global_load_lds_dwordx4 v[240:241], off
	v_lshl_add_u64 v[240:241], s[72:73], 0, v[132:133]
	s_add_i32 m0, s41, 0x2000
	s_nop 0
	global_load_lds_dwordx4 v[240:241], off
	v_lshl_add_u64 v[240:241], s[52:53], 0, v[148:149]
	s_mov_b32 m0, s27
	s_nop 0
	global_load_lds_dwordx4 v[240:241], off
	s_mov_b32 m0, s74
	s_nop 0
	global_load_lds_dwordx4 v[242:243], off
	s_waitcnt vmcnt(24)
	s_waitcnt lgkmcnt(0)
	s_barrier
	s_setprio 1
	s_waitcnt lgkmcnt(0)
	v_mfma_f32_16x16x32_bf16 v[62:65], v[154:157], v[206:209], v[62:65]
	v_mfma_f32_16x16x32_bf16 v[58:61], v[182:185], v[206:209], v[58:61]
	v_mfma_f32_16x16x32_bf16 v[50:53], v[154:157], v[214:217], v[50:53]
	v_mfma_f32_16x16x32_bf16 v[42:45], v[182:185], v[214:217], v[42:45]
	v_mfma_f32_16x16x32_bf16 v[34:37], v[154:157], v[222:225], v[34:37]
	v_mfma_f32_16x16x32_bf16 v[26:29], v[182:185], v[222:225], v[26:29]
	v_mfma_f32_16x16x32_bf16 v[18:21], v[154:157], v[230:233], v[18:21]
	v_mfma_f32_16x16x32_bf16 v[10:13], v[182:185], v[230:233], v[10:13]
	v_mfma_f32_16x16x32_bf16 v[62:65], v[178:181], v[210:213], v[62:65]
	v_mfma_f32_16x16x32_bf16 v[58:61], v[186:189], v[210:213], v[58:61]
	v_mfma_f32_16x16x32_bf16 v[50:53], v[178:181], v[218:221], v[50:53]
	v_mfma_f32_16x16x32_bf16 v[42:45], v[186:189], v[218:221], v[42:45]
	v_mfma_f32_16x16x32_bf16 v[34:37], v[178:181], v[226:229], v[34:37]
	v_mfma_f32_16x16x32_bf16 v[26:29], v[186:189], v[226:229], v[26:29]
	v_mfma_f32_16x16x32_bf16 v[18:21], v[178:181], v[234:237], v[18:21]
	v_mfma_f32_16x16x32_bf16 v[10:13], v[186:189], v[234:237], v[10:13]
	s_setprio 0
	s_setprio 1
	v_mfma_f32_16x16x32_bf16 v[54:57], v[190:193], v[206:209], v[54:57]
	v_mfma_f32_16x16x32_bf16 v[46:49], v[198:201], v[206:209], v[46:49]
	v_mfma_f32_16x16x32_bf16 v[38:41], v[190:193], v[214:217], v[38:41]
	v_mfma_f32_16x16x32_bf16 v[30:33], v[198:201], v[214:217], v[30:33]
	v_mfma_f32_16x16x32_bf16 v[22:25], v[190:193], v[222:225], v[22:25]
	v_mfma_f32_16x16x32_bf16 v[14:17], v[198:201], v[222:225], v[14:17]
	v_mfma_f32_16x16x32_bf16 v[6:9], v[190:193], v[230:233], v[6:9]
	v_mfma_f32_16x16x32_bf16 v[2:5], v[198:201], v[230:233], v[2:5]
	v_mfma_f32_16x16x32_bf16 v[54:57], v[194:197], v[210:213], v[54:57]
	v_mfma_f32_16x16x32_bf16 v[46:49], v[202:205], v[210:213], v[46:49]
	v_mfma_f32_16x16x32_bf16 v[38:41], v[194:197], v[218:221], v[38:41]
	v_mfma_f32_16x16x32_bf16 v[30:33], v[202:205], v[218:221], v[30:33]
	s_setprio 2
	s_barrier
	v_mfma_f32_16x16x32_bf16 v[22:25], v[194:197], v[226:229], v[22:25]
	v_mfma_f32_16x16x32_bf16 v[14:17], v[202:205], v[226:229], v[14:17]
	v_mfma_f32_16x16x32_bf16 v[6:9], v[194:197], v[234:237], v[6:9]
	v_mfma_f32_16x16x32_bf16 v[2:5], v[202:205], v[234:237], v[2:5]
	s_setprio 0
	s_add_i32 s41, 0, 0x18000
	v_add_u32_e32 v162, s41, v159
	s_add_i32 s72, 0, 0x1c000
	ds_read_b128 v[154:157], v162
	ds_read_b128 v[178:181], v162 offset:1024
	ds_read_b128 v[182:185], v162 offset:2048
	ds_read_b128 v[186:189], v162 offset:3072
	v_add_u32_e32 v162, s72, v159
	ds_read_b128 v[190:193], v162
	ds_read_b128 v[194:197], v162 offset:1024
	ds_read_b128 v[198:201], v162 offset:2048
	ds_read_b128 v[202:205], v162 offset:3072
	s_add_u32 s52, s52, 0x40000
	s_addc_u32 s53, s53, 0
	s_mov_b32 m0, s75
	v_lshl_add_u64 v[244:245], s[52:53], 0, v[148:149]
	ds_read_b128 v[206:209], v161 offset:32768
	ds_read_b128 v[210:213], v161 offset:33792
	ds_read_b128 v[214:217], v161 offset:34816
	ds_read_b128 v[218:221], v161 offset:35840
	ds_read_b128 v[222:225], v161 offset:36864
	ds_read_b128 v[226:229], v161 offset:37888
	ds_read_b128 v[230:233], v161 offset:38912
	ds_read_b128 v[234:237], v161 offset:39936
	global_load_lds_dwordx4 v[244:245], off
	v_lshl_add_u64 v[244:245], s[52:53], 0, v[144:145]
	s_mov_b32 m0, s97
	s_nop 0
	global_load_lds_dwordx4 v[244:245], off
	s_waitcnt vmcnt(8)
	s_waitcnt lgkmcnt(0)
	s_barrier
	s_setprio 1
	s_waitcnt lgkmcnt(0)
	v_mfma_f32_16x16x32_bf16 v[126:129], v[154:157], v[206:209], v[126:129]
	v_mfma_f32_16x16x32_bf16 v[122:125], v[182:185], v[206:209], v[122:125]
	v_mfma_f32_16x16x32_bf16 v[114:117], v[154:157], v[214:217], v[114:117]
	v_mfma_f32_16x16x32_bf16 v[106:109], v[182:185], v[214:217], v[106:109]
	v_mfma_f32_16x16x32_bf16 v[98:101], v[154:157], v[222:225], v[98:101]
	v_mfma_f32_16x16x32_bf16 v[90:93], v[182:185], v[222:225], v[90:93]
	v_mfma_f32_16x16x32_bf16 v[82:85], v[154:157], v[230:233], v[82:85]
	v_mfma_f32_16x16x32_bf16 v[74:77], v[182:185], v[230:233], v[74:77]
	v_mfma_f32_16x16x32_bf16 v[126:129], v[178:181], v[210:213], v[126:129]
	v_mfma_f32_16x16x32_bf16 v[122:125], v[186:189], v[210:213], v[122:125]
	v_mfma_f32_16x16x32_bf16 v[114:117], v[178:181], v[218:221], v[114:117]
	v_mfma_f32_16x16x32_bf16 v[106:109], v[186:189], v[218:221], v[106:109]
	v_mfma_f32_16x16x32_bf16 v[98:101], v[178:181], v[226:229], v[98:101]
	v_mfma_f32_16x16x32_bf16 v[90:93], v[186:189], v[226:229], v[90:93]
	v_mfma_f32_16x16x32_bf16 v[82:85], v[178:181], v[234:237], v[82:85]
	v_mfma_f32_16x16x32_bf16 v[74:77], v[186:189], v[234:237], v[74:77]
	s_setprio 0
	s_setprio 1
	v_mfma_f32_16x16x32_bf16 v[118:121], v[190:193], v[206:209], v[118:121]
	v_mfma_f32_16x16x32_bf16 v[110:113], v[198:201], v[206:209], v[110:113]
	v_mfma_f32_16x16x32_bf16 v[102:105], v[190:193], v[214:217], v[102:105]
	v_mfma_f32_16x16x32_bf16 v[94:97], v[198:201], v[214:217], v[94:97]
	v_mfma_f32_16x16x32_bf16 v[86:89], v[190:193], v[222:225], v[86:89]
	v_mfma_f32_16x16x32_bf16 v[78:81], v[198:201], v[222:225], v[78:81]
	v_mfma_f32_16x16x32_bf16 v[70:73], v[190:193], v[230:233], v[70:73]
	v_mfma_f32_16x16x32_bf16 v[66:69], v[198:201], v[230:233], v[66:69]
	v_mfma_f32_16x16x32_bf16 v[118:121], v[194:197], v[210:213], v[118:121]
	v_mfma_f32_16x16x32_bf16 v[110:113], v[202:205], v[210:213], v[110:113]
	v_mfma_f32_16x16x32_bf16 v[102:105], v[194:197], v[218:221], v[102:105]
	v_mfma_f32_16x16x32_bf16 v[94:97], v[202:205], v[218:221], v[94:97]
	s_setprio 2
	s_barrier
	v_mfma_f32_16x16x32_bf16 v[86:89], v[194:197], v[226:229], v[86:89]
	v_mfma_f32_16x16x32_bf16 v[78:81], v[202:205], v[226:229], v[78:81]
	v_mfma_f32_16x16x32_bf16 v[70:73], v[194:197], v[234:237], v[70:73]
	v_mfma_f32_16x16x32_bf16 v[66:69], v[202:205], v[234:237], v[66:69]
	s_setprio 0
	s_add_i32 s41, s41, s65
	v_lshl_add_u64 v[164:165], v[164:165], 0, s[66:67]
	s_mov_b32 m0, s41
	ds_read_b128 v[206:209], v161 offset:49152
	ds_read_b128 v[210:213], v161 offset:50176
	ds_read_b128 v[214:217], v161 offset:51200
	ds_read_b128 v[218:221], v161 offset:52224
	ds_read_b128 v[222:225], v161 offset:53248
	ds_read_b128 v[226:229], v161 offset:54272
	ds_read_b128 v[230:233], v161 offset:55296
	ds_read_b128 v[234:237], v161 offset:56320
	global_load_lds_dwordx4 v[164:165], off
	s_add_i32 m0, s41, 0x2000
	s_add_u32 s50, s50, 0x40080
	v_lshl_add_u64 v[164:165], v[238:239], 0, s[66:67]
	s_addc_u32 s51, s51, 0
	s_add_i32 s41, s72, s65
	global_load_lds_dwordx4 v[164:165], off
	v_lshl_add_u64 v[164:165], s[50:51], 0, v[146:147]
	s_mov_b32 m0, s41
	s_nop 0
	global_load_lds_dwordx4 v[164:165], off
	v_lshl_add_u64 v[164:165], s[50:51], 0, v[132:133]
	s_add_i32 m0, s41, 0x2000
	s_nop 0
	global_load_lds_dwordx4 v[164:165], off
	v_lshl_add_u64 v[164:165], v[240:241], 0, s[66:67]
	s_mov_b32 m0, s24
	s_nop 0
	global_load_lds_dwordx4 v[164:165], off
	v_lshl_add_u64 v[164:165], v[242:243], 0, s[66:67]
	s_mov_b32 m0, s25
	s_nop 0
	global_load_lds_dwordx4 v[164:165], off
	s_waitcnt vmcnt(8)
	s_waitcnt lgkmcnt(0)
	s_barrier
	s_setprio 1
	s_waitcnt lgkmcnt(0)
	v_mfma_f32_16x16x32_bf16 v[62:65], v[154:157], v[206:209], v[62:65]
	v_mfma_f32_16x16x32_bf16 v[58:61], v[182:185], v[206:209], v[58:61]
	v_mfma_f32_16x16x32_bf16 v[50:53], v[154:157], v[214:217], v[50:53]
	v_mfma_f32_16x16x32_bf16 v[42:45], v[182:185], v[214:217], v[42:45]
	v_mfma_f32_16x16x32_bf16 v[34:37], v[154:157], v[222:225], v[34:37]
	v_mfma_f32_16x16x32_bf16 v[26:29], v[182:185], v[222:225], v[26:29]
	v_mfma_f32_16x16x32_bf16 v[18:21], v[154:157], v[230:233], v[18:21]
	v_mfma_f32_16x16x32_bf16 v[10:13], v[182:185], v[230:233], v[10:13]
	v_mfma_f32_16x16x32_bf16 v[62:65], v[178:181], v[210:213], v[62:65]
	v_mfma_f32_16x16x32_bf16 v[58:61], v[186:189], v[210:213], v[58:61]
	v_mfma_f32_16x16x32_bf16 v[50:53], v[178:181], v[218:221], v[50:53]
	v_mfma_f32_16x16x32_bf16 v[42:45], v[186:189], v[218:221], v[42:45]
	v_mfma_f32_16x16x32_bf16 v[34:37], v[178:181], v[226:229], v[34:37]
	v_mfma_f32_16x16x32_bf16 v[26:29], v[186:189], v[226:229], v[26:29]
	v_mfma_f32_16x16x32_bf16 v[18:21], v[178:181], v[234:237], v[18:21]
	v_mfma_f32_16x16x32_bf16 v[10:13], v[186:189], v[234:237], v[10:13]
	s_setprio 0
	s_setprio 1
	v_mfma_f32_16x16x32_bf16 v[54:57], v[190:193], v[206:209], v[54:57]
	v_mfma_f32_16x16x32_bf16 v[46:49], v[198:201], v[206:209], v[46:49]
	v_mfma_f32_16x16x32_bf16 v[38:41], v[190:193], v[214:217], v[38:41]
	v_mfma_f32_16x16x32_bf16 v[30:33], v[198:201], v[214:217], v[30:33]
	v_mfma_f32_16x16x32_bf16 v[22:25], v[190:193], v[222:225], v[22:25]
	v_mfma_f32_16x16x32_bf16 v[14:17], v[198:201], v[222:225], v[14:17]
	v_mfma_f32_16x16x32_bf16 v[6:9], v[190:193], v[230:233], v[6:9]
	v_mfma_f32_16x16x32_bf16 v[2:5], v[198:201], v[230:233], v[2:5]
	v_mfma_f32_16x16x32_bf16 v[54:57], v[194:197], v[210:213], v[54:57]
	v_mfma_f32_16x16x32_bf16 v[46:49], v[202:205], v[210:213], v[46:49]
	v_mfma_f32_16x16x32_bf16 v[38:41], v[194:197], v[218:221], v[38:41]
	v_mfma_f32_16x16x32_bf16 v[30:33], v[202:205], v[218:221], v[30:33]
	s_setprio 2
	s_barrier
	v_mfma_f32_16x16x32_bf16 v[22:25], v[194:197], v[226:229], v[22:25]
	v_mfma_f32_16x16x32_bf16 v[14:17], v[202:205], v[226:229], v[14:17]
	v_mfma_f32_16x16x32_bf16 v[6:9], v[194:197], v[234:237], v[6:9]
	v_mfma_f32_16x16x32_bf16 v[2:5], v[202:205], v[234:237], v[2:5]
	s_setprio 0
	s_add_i32 s71, s71, 2
	s_add_u32 s98, s98, 0x100
	s_addc_u32 s99, s99, 0
	s_add_u32 vcc_hi, vcc_hi, 0x100
	s_addc_u32 s70, s70, 0
	s_cmp_gt_u32 s71, 13

.LBB0_304:
	v_lshl_add_u64 v[8:9], s[22:23], 0, v[134:135]
	v_mov_b32_e32 v133, v135
	v_lshl_add_u64 v[10:11], s[22:23], 0, v[132:133]
	v_mov_b32_e32 v147, v135
	s_add_i32 m0, s45, 0x18000
	v_lshl_add_u64 v[8:9], v[8:9], 0, s[66:67]
	v_lshl_add_u64 v[16:17], s[12:13], 0, v[146:147]
	v_mov_b32_e32 v145, v135
	s_waitcnt vmcnt(2)
	s_barrier
	global_load_lds_dwordx4 v[8:9], off
	v_lshl_add_u64 v[8:9], v[10:11], 0, s[66:67]
	s_add_i32 m0, s45, 0x1a000
	s_add_i32 s51, s45, 0x8000
	v_lshl_add_u64 v[18:19], s[12:13], 0, v[144:145]
	global_load_lds_dwordx4 v[8:9], off
	v_lshl_add_u64 v[8:9], v[16:17], 0, s[66:67]
	s_mov_b32 m0, s51
	s_add_i32 s52, s45, 0xa000
	v_lshl_add_u64 v[12:13], s[6:7], 0, v[134:135]
	global_load_lds_dwordx4 v[8:9], off
	v_lshl_add_u64 v[8:9], v[18:19], 0, s[66:67]
	s_mov_b32 m0, s52
	v_lshl_add_u64 v[14:15], s[6:7], 0, v[132:133]
	global_load_lds_dwordx4 v[8:9], off
	s_add_i32 m0, s45, 0x1c000
	v_lshl_add_u64 v[8:9], v[12:13], 0, s[66:67]
	global_load_lds_dwordx4 v[8:9], off
	v_lshl_add_u64 v[8:9], v[14:15], 0, s[66:67]
	s_add_i32 m0, s45, 0x1e000
	s_and_b32 s53, s9, 3
	global_load_lds_dwordx4 v[8:9], off
	v_bfe_u32 v8, v130, 4, 2
	v_and_b32_e32 v9, 15, v130
	v_lshlrev_b32_e32 v11, 4, v8
	v_lshl_or_b32 v131, s5, 6, v9
	v_lshl_or_b32 v9, v9, 6, v11
	v_lshlrev_b32_e32 v11, 2, v130
	s_lshl_b32 s5, s5, 13
	v_and_b32_e32 v11, 32, v11
	s_lshr_b32 s4, s4, 6
	v_bitop3_b32 v12, v9, s5, v11 bitop3:0xde
	s_lshl_b32 s5, s53, 12
	v_bitop3_b32 v159, s5, v9, v11 bitop3:0xf6
	s_waitcnt vmcnt(6)
	s_add_i32 s5, s4, -2
	v_add_u32_e32 v5, v7, v5
	v_add_u32_e32 v2, v4, v2
	v_lshlrev_b32_e32 v10, 3, v8
	s_cmpk_lt_u32 s8, 0x100
	v_add_lshl_u32 v6, v5, v6, 1
	v_mov_b32_e32 v7, v135
	v_add_lshl_u32 v2, v2, v3, 1
	v_mov_b32_e32 v3, v135
	v_lshl_or_b32 v160, s53, 5, v10
	s_cselect_b64 s[96:97], -1, 0
	s_mov_b32 s64, 0
	v_cmp_eq_u32_e64 s[6:7], 0, v8
	v_lshl_add_u64 v[148:149], s[92:93], 0, v[6:7]
	v_lshl_add_u64 v[150:151], s[92:93], 0, v[2:3]
	v_add_u32_e32 v161, 0, v12
	v_readlane_b32 s19, v254, 28
	v_readlane_b32 s21, v254, 27
	s_barrier
	v_writelane_b32 v253, 0, 0
	s_branch .LBB0_307

.LBB0_306:
	v_writelane_b32 v253, 1, 0
	s_andn2_b64 vcc, exec, s[8:9]
	s_mov_b32 s19, s93
	s_mov_b32 s21, s31
	s_mov_b64 s[22:23], s[98:99]
	s_mov_b64 s[12:13], s[10:11]
	s_cbranch_vccz .LBB0_340

.LBB0_317:
	s_add_u32 s12, s12, 0x80
	s_addc_u32 s13, s13, 0
	s_add_u32 s24, s22, 0x100
	v_mov_b32_e32 v2, 0
	s_addc_u32 s25, s23, 0
	s_mov_b32 s22, 0
	v_mov_b32_e32 v3, v2
	v_mov_b32_e32 v4, v2
	v_mov_b32_e32 v5, v2
	v_mov_b32_e32 v6, v2
	v_mov_b32_e32 v7, v2
	v_mov_b32_e32 v8, v2
	v_mov_b32_e32 v9, v2
	v_mov_b32_e32 v18, v2
	v_mov_b32_e32 v19, v2
	v_mov_b32_e32 v20, v2
	v_mov_b32_e32 v21, v2
	v_mov_b32_e32 v22, v2
	v_mov_b32_e32 v23, v2
	v_mov_b32_e32 v24, v2
	v_mov_b32_e32 v25, v2
	v_mov_b32_e32 v34, v2
	v_mov_b32_e32 v35, v2
	v_mov_b32_e32 v36, v2
	v_mov_b32_e32 v37, v2
	v_mov_b32_e32 v38, v2
	v_mov_b32_e32 v39, v2
	v_mov_b32_e32 v40, v2
	v_mov_b32_e32 v41, v2
	v_mov_b32_e32 v50, v2
	v_mov_b32_e32 v51, v2
	v_mov_b32_e32 v52, v2
	v_mov_b32_e32 v53, v2
	v_mov_b32_e32 v54, v2
	v_mov_b32_e32 v55, v2
	v_mov_b32_e32 v56, v2
	v_mov_b32_e32 v57, v2
	v_mov_b32_e32 v10, v2
	v_mov_b32_e32 v11, v2
	v_mov_b32_e32 v12, v2
	v_mov_b32_e32 v13, v2
	v_mov_b32_e32 v14, v2
	v_mov_b32_e32 v15, v2
	v_mov_b32_e32 v16, v2
	v_mov_b32_e32 v17, v2
	v_mov_b32_e32 v26, v2
	v_mov_b32_e32 v27, v2
	v_mov_b32_e32 v28, v2
	v_mov_b32_e32 v29, v2
	v_mov_b32_e32 v30, v2
	v_mov_b32_e32 v31, v2
	v_mov_b32_e32 v32, v2
	v_mov_b32_e32 v33, v2
	v_mov_b32_e32 v42, v2
	v_mov_b32_e32 v43, v2
	v_mov_b32_e32 v44, v2
	v_mov_b32_e32 v45, v2
	v_mov_b32_e32 v46, v2
	v_mov_b32_e32 v47, v2
	v_mov_b32_e32 v48, v2
	v_mov_b32_e32 v49, v2
	v_mov_b32_e32 v58, v2
	v_mov_b32_e32 v59, v2
	v_mov_b32_e32 v60, v2
	v_mov_b32_e32 v61, v2
	v_mov_b32_e32 v62, v2
	v_mov_b32_e32 v63, v2
	v_mov_b32_e32 v64, v2
	v_mov_b32_e32 v65, v2
	v_mov_b32_e32 v66, v2
	v_mov_b32_e32 v67, v2
	v_mov_b32_e32 v68, v2
	v_mov_b32_e32 v69, v2
	v_mov_b32_e32 v70, v2
	v_mov_b32_e32 v71, v2
	v_mov_b32_e32 v72, v2
	v_mov_b32_e32 v73, v2
	v_mov_b32_e32 v82, v2
	v_mov_b32_e32 v83, v2
	v_mov_b32_e32 v84, v2
	v_mov_b32_e32 v85, v2
	v_mov_b32_e32 v86, v2
	v_mov_b32_e32 v87, v2
	v_mov_b32_e32 v88, v2
	v_mov_b32_e32 v89, v2
	v_mov_b32_e32 v98, v2
	v_mov_b32_e32 v99, v2
	v_mov_b32_e32 v100, v2
	v_mov_b32_e32 v101, v2
	v_mov_b32_e32 v102, v2
	v_mov_b32_e32 v103, v2
	v_mov_b32_e32 v104, v2
	v_mov_b32_e32 v105, v2
	v_mov_b32_e32 v114, v2
	v_mov_b32_e32 v115, v2
	v_mov_b32_e32 v116, v2
	v_mov_b32_e32 v117, v2
	v_mov_b32_e32 v118, v2
	v_mov_b32_e32 v119, v2
	v_mov_b32_e32 v120, v2
	v_mov_b32_e32 v121, v2
	v_mov_b32_e32 v74, v2
	v_mov_b32_e32 v75, v2
	v_mov_b32_e32 v76, v2
	v_mov_b32_e32 v77, v2
	v_mov_b32_e32 v78, v2
	v_mov_b32_e32 v79, v2
	v_mov_b32_e32 v80, v2
	v_mov_b32_e32 v81, v2
	v_mov_b32_e32 v90, v2
	v_mov_b32_e32 v91, v2
	v_mov_b32_e32 v92, v2
	v_mov_b32_e32 v93, v2
	v_mov_b32_e32 v94, v2
	v_mov_b32_e32 v95, v2
	v_mov_b32_e32 v96, v2
	v_mov_b32_e32 v97, v2
	v_mov_b32_e32 v106, v2
	v_mov_b32_e32 v107, v2
	v_mov_b32_e32 v108, v2
	v_mov_b32_e32 v109, v2
	v_mov_b32_e32 v110, v2
	v_mov_b32_e32 v111, v2
	v_mov_b32_e32 v112, v2
	v_mov_b32_e32 v113, v2
	v_mov_b32_e32 v122, v2
	v_mov_b32_e32 v123, v2
	v_mov_b32_e32 v124, v2
	v_mov_b32_e32 v125, v2
	v_mov_b32_e32 v126, v2
	v_mov_b32_e32 v127, v2
	v_mov_b32_e32 v128, v2
	v_mov_b32_e32 v129, v2
	v_readlane_b32 s30, v253, 0
	s_nop 1
	s_cmp_eq_u32 s30, 0
	s_cbranch_scc1 .LBB0_318
	s_add_i32 s30, s22, 2
	s_add_u32 s37, s12, 0x80
	s_addc_u32 s23, s13, 0
	s_add_i32 s56, 0, 0x10000
	s_cmp_eq_u32 s5, s22
	s_cselect_b32 s23, s11, s23
	s_cselect_b32 s22, s10, s37
	v_add_u32_e32 v156, s56, v159
	s_cselect_b32 s69, s99, s25
	s_cselect_b32 s68, s98, s24
	s_add_i32 s37, 0, 0x14000
	ds_read_b128 v[152:155], v156
	ds_read_b128 v[178:181], v156 offset:1024
	ds_read_b128 v[182:185], v156 offset:2048
	ds_read_b128 v[186:189], v156 offset:3072
	v_add_u32_e32 v156, s37, v159
	ds_read_b128 v[190:193], v156
	ds_read_b128 v[194:197], v156 offset:1024
	ds_read_b128 v[198:201], v156 offset:2048
	ds_read_b128 v[202:205], v156 offset:3072
	v_lshl_add_u64 v[156:157], s[12:13], 0, v[148:149]
	s_add_i32 m0, s45, 0xc000
	ds_read_b128 v[206:209], v161
	ds_read_b128 v[210:213], v161 offset:1024
	ds_read_b128 v[214:217], v161 offset:2048
	ds_read_b128 v[218:221], v161 offset:3072
	ds_read_b128 v[222:225], v161 offset:4096
	ds_read_b128 v[226:229], v161 offset:5120
	ds_read_b128 v[230:233], v161 offset:6144
	ds_read_b128 v[234:237], v161 offset:7168
	global_load_lds_dwordx4 v[156:157], off
	v_lshl_add_u64 v[156:157], s[12:13], 0, v[150:151]
	s_add_i32 m0, s45, 0xe000
	s_nop 0
	global_load_lds_dwordx4 v[156:157], off
	s_waitcnt vmcnt(32)
	s_waitcnt lgkmcnt(0)
	s_barrier
	s_setprio 1
	s_waitcnt lgkmcnt(0)
	v_mfma_f32_16x16x32_bf16 v[126:129], v[152:155], v[206:209], v[126:129]
	v_mfma_f32_16x16x32_bf16 v[122:125], v[182:185], v[206:209], v[122:125]
	v_mfma_f32_16x16x32_bf16 v[110:113], v[152:155], v[214:217], v[110:113]
	v_mfma_f32_16x16x32_bf16 v[106:109], v[182:185], v[214:217], v[106:109]
	v_mfma_f32_16x16x32_bf16 v[94:97], v[152:155], v[222:225], v[94:97]
	v_mfma_f32_16x16x32_bf16 v[90:93], v[182:185], v[222:225], v[90:93]
	v_mfma_f32_16x16x32_bf16 v[78:81], v[152:155], v[230:233], v[78:81]
	v_mfma_f32_16x16x32_bf16 v[74:77], v[182:185], v[230:233], v[74:77]
	v_mfma_f32_16x16x32_bf16 v[126:129], v[178:181], v[210:213], v[126:129]
	v_mfma_f32_16x16x32_bf16 v[122:125], v[186:189], v[210:213], v[122:125]
	v_mfma_f32_16x16x32_bf16 v[110:113], v[178:181], v[218:221], v[110:113]
	v_mfma_f32_16x16x32_bf16 v[106:109], v[186:189], v[218:221], v[106:109]
	v_mfma_f32_16x16x32_bf16 v[94:97], v[178:181], v[226:229], v[94:97]
	v_mfma_f32_16x16x32_bf16 v[90:93], v[186:189], v[226:229], v[90:93]
	v_mfma_f32_16x16x32_bf16 v[78:81], v[178:181], v[234:237], v[78:81]
	v_mfma_f32_16x16x32_bf16 v[74:77], v[186:189], v[234:237], v[74:77]
	s_setprio 0
	s_setprio 1
	v_mfma_f32_16x16x32_bf16 v[118:121], v[190:193], v[206:209], v[118:121]
	v_mfma_f32_16x16x32_bf16 v[114:117], v[198:201], v[206:209], v[114:117]
	v_mfma_f32_16x16x32_bf16 v[102:105], v[190:193], v[214:217], v[102:105]
	v_mfma_f32_16x16x32_bf16 v[98:101], v[198:201], v[214:217], v[98:101]
	v_mfma_f32_16x16x32_bf16 v[86:89], v[190:193], v[222:225], v[86:89]
	v_mfma_f32_16x16x32_bf16 v[82:85], v[198:201], v[222:225], v[82:85]
	v_mfma_f32_16x16x32_bf16 v[70:73], v[190:193], v[230:233], v[70:73]
	v_mfma_f32_16x16x32_bf16 v[66:69], v[198:201], v[230:233], v[66:69]
	v_mfma_f32_16x16x32_bf16 v[118:121], v[194:197], v[210:213], v[118:121]
	v_mfma_f32_16x16x32_bf16 v[114:117], v[202:205], v[210:213], v[114:117]
	v_mfma_f32_16x16x32_bf16 v[102:105], v[194:197], v[218:221], v[102:105]
	v_mfma_f32_16x16x32_bf16 v[98:101], v[202:205], v[218:221], v[98:101]
	s_setprio 2
	s_barrier
	v_mfma_f32_16x16x32_bf16 v[86:89], v[194:197], v[226:229], v[86:89]
	v_mfma_f32_16x16x32_bf16 v[82:85], v[202:205], v[226:229], v[82:85]
	v_mfma_f32_16x16x32_bf16 v[70:73], v[194:197], v[234:237], v[70:73]
	v_mfma_f32_16x16x32_bf16 v[66:69], v[202:205], v[234:237], v[66:69]
	s_setprio 0
	s_add_i32 s56, s56, s26
	v_lshl_add_u64 v[156:157], s[68:69], 0, v[134:135]
	s_mov_b32 m0, s56
	ds_read_b128 v[206:209], v161 offset:16384
	ds_read_b128 v[210:213], v161 offset:17408
	ds_read_b128 v[214:217], v161 offset:18432
	ds_read_b128 v[218:221], v161 offset:19456
	ds_read_b128 v[222:225], v161 offset:20480
	ds_read_b128 v[226:229], v161 offset:21504
	ds_read_b128 v[230:233], v161 offset:22528
	ds_read_b128 v[234:237], v161 offset:23552
	global_load_lds_dwordx4 v[156:157], off
	s_add_i32 m0, s56, 0x2000
	v_lshl_add_u64 v[164:165], s[68:69], 0, v[132:133]
	s_add_u32 s68, s68, s92
	s_addc_u32 s69, s69, 0
	s_add_i32 s37, s37, s26
	global_load_lds_dwordx4 v[164:165], off
	v_lshl_add_u64 v[238:239], s[68:69], 0, v[134:135]
	s_mov_b32 m0, s37
	v_lshl_add_u64 v[240:241], s[68:69], 0, v[132:133]
	global_load_lds_dwordx4 v[238:239], off
	s_add_i32 m0, s37, 0x2000
	v_lshl_add_u64 v[242:243], s[22:23], 0, v[146:147]
	global_load_lds_dwordx4 v[240:241], off
	s_mov_b32 m0, s45
	v_lshl_add_u64 v[244:245], s[22:23], 0, v[144:145]
	global_load_lds_dwordx4 v[242:243], off
	s_mov_b32 m0, s46
	s_nop 0
	global_load_lds_dwordx4 v[244:245], off
	s_waitcnt vmcnt(32)
	s_waitcnt lgkmcnt(0)
	s_barrier
	s_setprio 1
	s_waitcnt lgkmcnt(0)
	v_mfma_f32_16x16x32_bf16 v[62:65], v[152:155], v[206:209], v[62:65]
	v_mfma_f32_16x16x32_bf16 v[58:61], v[182:185], v[206:209], v[58:61]
	v_mfma_f32_16x16x32_bf16 v[46:49], v[152:155], v[214:217], v[46:49]
	v_mfma_f32_16x16x32_bf16 v[42:45], v[182:185], v[214:217], v[42:45]
	v_mfma_f32_16x16x32_bf16 v[30:33], v[152:155], v[222:225], v[30:33]
	v_mfma_f32_16x16x32_bf16 v[26:29], v[182:185], v[222:225], v[26:29]
	v_mfma_f32_16x16x32_bf16 v[14:17], v[152:155], v[230:233], v[14:17]
	v_mfma_f32_16x16x32_bf16 v[10:13], v[182:185], v[230:233], v[10:13]
	v_mfma_f32_16x16x32_bf16 v[62:65], v[178:181], v[210:213], v[62:65]
	v_mfma_f32_16x16x32_bf16 v[58:61], v[186:189], v[210:213], v[58:61]
	v_mfma_f32_16x16x32_bf16 v[46:49], v[178:181], v[218:221], v[46:49]
	v_mfma_f32_16x16x32_bf16 v[42:45], v[186:189], v[218:221], v[42:45]
	v_mfma_f32_16x16x32_bf16 v[30:33], v[178:181], v[226:229], v[30:33]
	v_mfma_f32_16x16x32_bf16 v[26:29], v[186:189], v[226:229], v[26:29]
	v_mfma_f32_16x16x32_bf16 v[14:17], v[178:181], v[234:237], v[14:17]
	v_mfma_f32_16x16x32_bf16 v[10:13], v[186:189], v[234:237], v[10:13]
	s_setprio 0
	s_setprio 1
	v_mfma_f32_16x16x32_bf16 v[54:57], v[190:193], v[206:209], v[54:57]
	v_mfma_f32_16x16x32_bf16 v[50:53], v[198:201], v[206:209], v[50:53]
	v_mfma_f32_16x16x32_bf16 v[38:41], v[190:193], v[214:217], v[38:41]
	v_mfma_f32_16x16x32_bf16 v[34:37], v[198:201], v[214:217], v[34:37]
	v_mfma_f32_16x16x32_bf16 v[22:25], v[190:193], v[222:225], v[22:25]
	v_mfma_f32_16x16x32_bf16 v[18:21], v[198:201], v[222:225], v[18:21]
	v_mfma_f32_16x16x32_bf16 v[6:9], v[190:193], v[230:233], v[6:9]
	v_mfma_f32_16x16x32_bf16 v[2:5], v[198:201], v[230:233], v[2:5]
	v_mfma_f32_16x16x32_bf16 v[54:57], v[194:197], v[210:213], v[54:57]
	v_mfma_f32_16x16x32_bf16 v[50:53], v[202:205], v[210:213], v[50:53]
	v_mfma_f32_16x16x32_bf16 v[38:41], v[194:197], v[218:221], v[38:41]
	v_mfma_f32_16x16x32_bf16 v[34:37], v[202:205], v[218:221], v[34:37]
	s_setprio 2
	s_barrier
	v_mfma_f32_16x16x32_bf16 v[22:25], v[194:197], v[226:229], v[22:25]
	v_mfma_f32_16x16x32_bf16 v[18:21], v[202:205], v[226:229], v[18:21]
	v_mfma_f32_16x16x32_bf16 v[6:9], v[194:197], v[234:237], v[6:9]
	v_mfma_f32_16x16x32_bf16 v[2:5], v[202:205], v[234:237], v[2:5]
	s_setprio 0
	s_add_i32 s37, 0, 0x18000
	v_add_u32_e32 v162, s37, v159
	s_add_i32 s56, 0, 0x1c000
	ds_read_b128 v[152:155], v162
	ds_read_b128 v[178:181], v162 offset:1024
	ds_read_b128 v[182:185], v162 offset:2048
	ds_read_b128 v[186:189], v162 offset:3072
	v_add_u32_e32 v162, s56, v159
	ds_read_b128 v[190:193], v162
	ds_read_b128 v[194:197], v162 offset:1024
	ds_read_b128 v[198:201], v162 offset:2048
	ds_read_b128 v[202:205], v162 offset:3072
	s_add_u32 s22, s22, s92
	s_addc_u32 s23, s23, 0
	s_mov_b32 m0, s47
	v_lshl_add_u64 v[246:247], s[22:23], 0, v[146:147]
	ds_read_b128 v[206:209], v161 offset:32768
	ds_read_b128 v[210:213], v161 offset:33792
	ds_read_b128 v[214:217], v161 offset:34816
	ds_read_b128 v[218:221], v161 offset:35840
	ds_read_b128 v[222:225], v161 offset:36864
	ds_read_b128 v[226:229], v161 offset:37888
	ds_read_b128 v[230:233], v161 offset:38912
	ds_read_b128 v[234:237], v161 offset:39936
	global_load_lds_dwordx4 v[246:247], off
	v_lshl_add_u64 v[246:247], s[22:23], 0, v[144:145]
	s_mov_b32 m0, s50
	s_nop 0
	global_load_lds_dwordx4 v[246:247], off
	s_waitcnt vmcnt(8)
	s_waitcnt lgkmcnt(0)
	s_barrier
	s_setprio 1
	s_waitcnt lgkmcnt(0)
	v_mfma_f32_16x16x32_bf16 v[126:129], v[152:155], v[206:209], v[126:129]
	v_mfma_f32_16x16x32_bf16 v[122:125], v[182:185], v[206:209], v[122:125]
	v_mfma_f32_16x16x32_bf16 v[110:113], v[152:155], v[214:217], v[110:113]
	v_mfma_f32_16x16x32_bf16 v[106:109], v[182:185], v[214:217], v[106:109]
	v_mfma_f32_16x16x32_bf16 v[94:97], v[152:155], v[222:225], v[94:97]
	v_mfma_f32_16x16x32_bf16 v[90:93], v[182:185], v[222:225], v[90:93]
	v_mfma_f32_16x16x32_bf16 v[78:81], v[152:155], v[230:233], v[78:81]
	v_mfma_f32_16x16x32_bf16 v[74:77], v[182:185], v[230:233], v[74:77]
	v_mfma_f32_16x16x32_bf16 v[126:129], v[178:181], v[210:213], v[126:129]
	v_mfma_f32_16x16x32_bf16 v[122:125], v[186:189], v[210:213], v[122:125]
	v_mfma_f32_16x16x32_bf16 v[110:113], v[178:181], v[218:221], v[110:113]
	v_mfma_f32_16x16x32_bf16 v[106:109], v[186:189], v[218:221], v[106:109]
	v_mfma_f32_16x16x32_bf16 v[94:97], v[178:181], v[226:229], v[94:97]
	v_mfma_f32_16x16x32_bf16 v[90:93], v[186:189], v[226:229], v[90:93]
	v_mfma_f32_16x16x32_bf16 v[78:81], v[178:181], v[234:237], v[78:81]
	v_mfma_f32_16x16x32_bf16 v[74:77], v[186:189], v[234:237], v[74:77]
	s_setprio 0
	s_setprio 1
	v_mfma_f32_16x16x32_bf16 v[118:121], v[190:193], v[206:209], v[118:121]
	v_mfma_f32_16x16x32_bf16 v[114:117], v[198:201], v[206:209], v[114:117]
	v_mfma_f32_16x16x32_bf16 v[102:105], v[190:193], v[214:217], v[102:105]
	v_mfma_f32_16x16x32_bf16 v[98:101], v[198:201], v[214:217], v[98:101]
	v_mfma_f32_16x16x32_bf16 v[86:89], v[190:193], v[222:225], v[86:89]
	v_mfma_f32_16x16x32_bf16 v[82:85], v[198:201], v[222:225], v[82:85]
	v_mfma_f32_16x16x32_bf16 v[70:73], v[190:193], v[230:233], v[70:73]
	v_mfma_f32_16x16x32_bf16 v[66:69], v[198:201], v[230:233], v[66:69]
	v_mfma_f32_16x16x32_bf16 v[118:121], v[194:197], v[210:213], v[118:121]
	v_mfma_f32_16x16x32_bf16 v[114:117], v[202:205], v[210:213], v[114:117]
	v_mfma_f32_16x16x32_bf16 v[102:105], v[194:197], v[218:221], v[102:105]
	v_mfma_f32_16x16x32_bf16 v[98:101], v[202:205], v[218:221], v[98:101]
	s_setprio 2
	s_barrier
	v_mfma_f32_16x16x32_bf16 v[86:89], v[194:197], v[226:229], v[86:89]
	v_mfma_f32_16x16x32_bf16 v[82:85], v[202:205], v[226:229], v[82:85]
	v_mfma_f32_16x16x32_bf16 v[70:73], v[194:197], v[234:237], v[70:73]
	v_mfma_f32_16x16x32_bf16 v[66:69], v[202:205], v[234:237], v[66:69]
	s_setprio 0
	s_add_i32 s22, s37, s26
	v_lshl_add_u64 v[156:157], v[156:157], 0, s[66:67]
	s_mov_b32 m0, s22
	ds_read_b128 v[206:209], v161 offset:49152
	ds_read_b128 v[210:213], v161 offset:50176
	ds_read_b128 v[214:217], v161 offset:51200
	ds_read_b128 v[218:221], v161 offset:52224
	ds_read_b128 v[222:225], v161 offset:53248
	ds_read_b128 v[226:229], v161 offset:54272
	ds_read_b128 v[230:233], v161 offset:55296
	ds_read_b128 v[234:237], v161 offset:56320
	global_load_lds_dwordx4 v[156:157], off
	v_lshl_add_u64 v[156:157], v[164:165], 0, s[66:67]
	s_add_i32 m0, s22, 0x2000
	s_add_i32 s22, s56, s26
	global_load_lds_dwordx4 v[156:157], off
	v_lshl_add_u64 v[156:157], v[238:239], 0, s[66:67]
	s_mov_b32 m0, s22
	s_nop 0
	global_load_lds_dwordx4 v[156:157], off
	v_lshl_add_u64 v[156:157], v[240:241], 0, s[66:67]
	s_add_i32 m0, s22, 0x2000
	s_nop 0
	global_load_lds_dwordx4 v[156:157], off
	v_lshl_add_u64 v[156:157], v[242:243], 0, s[66:67]
	s_mov_b32 m0, s51
	s_nop 0
	global_load_lds_dwordx4 v[156:157], off
	v_lshl_add_u64 v[156:157], v[244:245], 0, s[66:67]
	s_mov_b32 m0, s52
	s_nop 0
	global_load_lds_dwordx4 v[156:157], off
	s_waitcnt vmcnt(8)
	s_waitcnt lgkmcnt(0)
	s_barrier
	s_setprio 1
	s_waitcnt lgkmcnt(0)
	v_mfma_f32_16x16x32_bf16 v[62:65], v[152:155], v[206:209], v[62:65]
	v_mfma_f32_16x16x32_bf16 v[58:61], v[182:185], v[206:209], v[58:61]
	v_mfma_f32_16x16x32_bf16 v[46:49], v[152:155], v[214:217], v[46:49]
	v_mfma_f32_16x16x32_bf16 v[42:45], v[182:185], v[214:217], v[42:45]
	v_mfma_f32_16x16x32_bf16 v[30:33], v[152:155], v[222:225], v[30:33]
	v_mfma_f32_16x16x32_bf16 v[26:29], v[182:185], v[222:225], v[26:29]
	v_mfma_f32_16x16x32_bf16 v[14:17], v[152:155], v[230:233], v[14:17]
	v_mfma_f32_16x16x32_bf16 v[10:13], v[182:185], v[230:233], v[10:13]
	v_mfma_f32_16x16x32_bf16 v[62:65], v[178:181], v[210:213], v[62:65]
	v_mfma_f32_16x16x32_bf16 v[58:61], v[186:189], v[210:213], v[58:61]
	v_mfma_f32_16x16x32_bf16 v[46:49], v[178:181], v[218:221], v[46:49]
	v_mfma_f32_16x16x32_bf16 v[42:45], v[186:189], v[218:221], v[42:45]
	v_mfma_f32_16x16x32_bf16 v[30:33], v[178:181], v[226:229], v[30:33]
	v_mfma_f32_16x16x32_bf16 v[26:29], v[186:189], v[226:229], v[26:29]
	v_mfma_f32_16x16x32_bf16 v[14:17], v[178:181], v[234:237], v[14:17]
	v_mfma_f32_16x16x32_bf16 v[10:13], v[186:189], v[234:237], v[10:13]
	s_setprio 0
	s_setprio 1
	v_mfma_f32_16x16x32_bf16 v[54:57], v[190:193], v[206:209], v[54:57]
	v_mfma_f32_16x16x32_bf16 v[50:53], v[198:201], v[206:209], v[50:53]
	v_mfma_f32_16x16x32_bf16 v[38:41], v[190:193], v[214:217], v[38:41]
	v_mfma_f32_16x16x32_bf16 v[34:37], v[198:201], v[214:217], v[34:37]
	v_mfma_f32_16x16x32_bf16 v[22:25], v[190:193], v[222:225], v[22:25]
	v_mfma_f32_16x16x32_bf16 v[18:21], v[198:201], v[222:225], v[18:21]
	v_mfma_f32_16x16x32_bf16 v[6:9], v[190:193], v[230:233], v[6:9]
	v_mfma_f32_16x16x32_bf16 v[2:5], v[198:201], v[230:233], v[2:5]
	v_mfma_f32_16x16x32_bf16 v[54:57], v[194:197], v[210:213], v[54:57]
	v_mfma_f32_16x16x32_bf16 v[50:53], v[202:205], v[210:213], v[50:53]
	v_mfma_f32_16x16x32_bf16 v[38:41], v[194:197], v[218:221], v[38:41]
	v_mfma_f32_16x16x32_bf16 v[34:37], v[202:205], v[218:221], v[34:37]
	s_setprio 2
	s_barrier
	v_mfma_f32_16x16x32_bf16 v[22:25], v[194:197], v[226:229], v[22:25]
	v_mfma_f32_16x16x32_bf16 v[18:21], v[202:205], v[226:229], v[18:21]
	v_mfma_f32_16x16x32_bf16 v[6:9], v[194:197], v[234:237], v[6:9]
	v_mfma_f32_16x16x32_bf16 v[2:5], v[202:205], v[234:237], v[2:5]
	s_setprio 0
	s_add_u32 s12, s12, 0x100
	s_addc_u32 s13, s13, 0
	s_add_u32 s24, s24, 0x100
	s_addc_u32 s25, s25, 0
	s_cmp_ge_u32 s30, s4
	s_mov_b32 s22, s30

.LBB0_406:
	s_add_u32 s10, s82, 0xf200000
	v_lshrrev_b32_e32 v17, 1, v130
	s_addc_u32 s11, s83, 0
	v_and_b32_e32 v17, 24, v17
	s_add_u32 s82, s82, 0x12200000
	v_and_b32_e32 v16, 15, v130
	v_lshlrev_b32_e32 v18, 1, v17
	s_addc_u32 s83, s83, 0
	v_lshl_or_b32 v153, s7, 6, v16
	v_lshl_or_b32 v18, v16, 6, v18
	v_lshlrev_b32_e32 v16, 2, v16
	s_lshl_b32 s19, s19, 5
	s_lshl_b32 s21, s7, 13
	v_and_b32_e32 v19, 32, v16
	s_and_b32 s19, s19, 0x60
	s_add_i32 m0, s31, 0x18000
	v_lshl_add_u64 v[8:9], v[8:9], 0, s[66:67]
	v_bitop3_b32 v20, v18, s21, v19 bitop3:0xde
	s_lshl_b32 s21, s19, 7
	s_waitcnt vmcnt(2)
	s_barrier
	global_load_lds_dwordx4 v[8:9], off
	v_lshl_add_u64 v[6:7], v[6:7], 0, s[66:67]
	s_add_i32 m0, s31, 0x1a000
	s_add_i32 s41, s31, 0x8000
	s_add_i32 s44, s31, 0xa000
	global_load_lds_dwordx4 v[6:7], off
	v_lshl_add_u64 v[2:3], v[2:3], 0, s[66:67]
	s_mov_b32 m0, s41
	s_add_u32 s24, s22, 0x40080
	global_load_lds_dwordx4 v[2:3], off
	v_lshl_add_u64 v[2:3], v[4:5], 0, s[66:67]
	s_mov_b32 m0, s44
	s_addc_u32 s25, s23, 0
	global_load_lds_dwordx4 v[2:3], off
	s_add_i32 m0, s31, 0x1c000
	v_lshl_add_u64 v[2:3], s[24:25], 0, v[148:149]
	global_load_lds_dwordx4 v[2:3], off
	v_lshl_add_u64 v[2:3], s[24:25], 0, v[144:145]
	s_add_i32 m0, s31, 0x1e000
	s_cmpk_lt_u32 s6, 0x100
	global_load_lds_dwordx4 v[2:3], off
	v_lshlrev_b32_e32 v2, 14, v14
	v_and_b32_e32 v2, 0xffff8000, v2
	v_lshl_add_u32 v2, v13, 11, v2
	v_and_b32_e32 v3, 1, v14
	v_lshl_or_b32 v2, v3, 6, v2
	s_cselect_b64 s[84:85], -1, 0
	s_lshl_b32 s6, s7, 8
	v_lshl_add_u32 v156, v15, 1, v2
	v_lshlrev_b32_e32 v2, 14, v10
	s_add_i32 s6, s6, 0
	v_and_b32_e32 v2, 0xffff8000, v2
	s_waitcnt vmcnt(6)
	v_or_b32_e32 v152, s19, v17
	s_add_i32 s6, s6, 0x20400
	v_lshl_add_u32 v2, v11, 11, v2
	v_and_b32_e32 v3, 1, v10
	v_add_u32_e32 v179, s6, v16
	v_lshlrev_b32_e32 v134, 1, v152
	v_lshl_or_b32 v2, v3, 6, v2
	v_readlane_b32 s6, v254, 32
	v_bitop3_b32 v178, s21, v18, v19 bitop3:0xf6
	v_lshl_add_u64 v[154:155], s[82:83], 0, v[134:135]
	v_mov_b32_e32 v157, v135
	v_lshl_add_u32 v158, v12, 1, v2
	v_mov_b32_e32 v159, v135
	s_mov_b32 s21, 0
	v_add_u32_e32 v180, 0, v20
	v_readlane_b32 s19, v254, 31
	s_mov_b32 s24, s6
	s_mov_b32 s45, 0
	s_barrier
	v_readlane_b32 s7, v254, 33
	v_writelane_b32 v253, 0, 0
	s_branch .LBB0_409

.LBB0_408:
	v_writelane_b32 v253, 1, 0
	s_andn2_b64 vcc, exec, s[6:7]
	s_mov_b32 s21, s46
	s_mov_b32 s19, s86
	s_mov_b32 s24, s88
	s_mov_b64 s[22:23], s[92:93]
	s_mov_b64 s[12:13], s[90:91]
	s_cbranch_vccz .LBB0_426

.LBB0_411:
	s_ashr_i32 s89, s88, 31
	s_lshl_b64 s[26:27], s[88:89], 19
	s_add_u32 s90, s78, s26
	s_addc_u32 s91, s79, s27
	s_and_b64 s[26:27], s[6:7], exec
	s_cselect_b32 s25, s91, s13
	s_cselect_b32 s30, s90, s12
	s_ashr_i32 s87, s86, 31
	s_lshl_b64 s[26:27], s[86:87], 19
	s_add_u32 s92, s4, s26
	s_addc_u32 s93, s5, s27
	s_and_b64 s[26:27], s[6:7], exec
	s_cselect_b32 s37, s93, s23
	s_cselect_b32 s47, s92, s22
	s_add_u32 s12, s12, 0x40080
	s_addc_u32 s13, s13, 0
	s_add_u32 s50, s22, 0x100
	v_mov_b32_e32 v2, 0
	s_addc_u32 s51, s23, 0
	s_mov_b32 s52, -2
	v_mov_b32_e32 v3, v2
	v_mov_b32_e32 v4, v2
	v_mov_b32_e32 v5, v2
	v_mov_b32_e32 v6, v2
	v_mov_b32_e32 v7, v2
	v_mov_b32_e32 v8, v2
	v_mov_b32_e32 v9, v2
	v_mov_b32_e32 v14, v2
	v_mov_b32_e32 v15, v2
	v_mov_b32_e32 v16, v2
	v_mov_b32_e32 v17, v2
	v_mov_b32_e32 v22, v2
	v_mov_b32_e32 v23, v2
	v_mov_b32_e32 v24, v2
	v_mov_b32_e32 v25, v2
	v_mov_b32_e32 v30, v2
	v_mov_b32_e32 v31, v2
	v_mov_b32_e32 v32, v2
	v_mov_b32_e32 v33, v2
	v_mov_b32_e32 v38, v2
	v_mov_b32_e32 v39, v2
	v_mov_b32_e32 v40, v2
	v_mov_b32_e32 v41, v2
	v_mov_b32_e32 v46, v2
	v_mov_b32_e32 v47, v2
	v_mov_b32_e32 v48, v2
	v_mov_b32_e32 v49, v2
	v_mov_b32_e32 v54, v2
	v_mov_b32_e32 v55, v2
	v_mov_b32_e32 v56, v2
	v_mov_b32_e32 v57, v2
	v_mov_b32_e32 v10, v2
	v_mov_b32_e32 v11, v2
	v_mov_b32_e32 v12, v2
	v_mov_b32_e32 v13, v2
	v_mov_b32_e32 v18, v2
	v_mov_b32_e32 v19, v2
	v_mov_b32_e32 v20, v2
	v_mov_b32_e32 v21, v2
	v_mov_b32_e32 v26, v2
	v_mov_b32_e32 v27, v2
	v_mov_b32_e32 v28, v2
	v_mov_b32_e32 v29, v2
	v_mov_b32_e32 v34, v2
	v_mov_b32_e32 v35, v2
	v_mov_b32_e32 v36, v2
	v_mov_b32_e32 v37, v2
	v_mov_b32_e32 v42, v2
	v_mov_b32_e32 v43, v2
	v_mov_b32_e32 v44, v2
	v_mov_b32_e32 v45, v2
	v_mov_b32_e32 v50, v2
	v_mov_b32_e32 v51, v2
	v_mov_b32_e32 v52, v2
	v_mov_b32_e32 v53, v2
	v_mov_b32_e32 v58, v2
	v_mov_b32_e32 v59, v2
	v_mov_b32_e32 v60, v2
	v_mov_b32_e32 v61, v2
	v_mov_b32_e32 v62, v2
	v_mov_b32_e32 v63, v2
	v_mov_b32_e32 v64, v2
	v_mov_b32_e32 v65, v2
	v_mov_b32_e32 v66, v2
	v_mov_b32_e32 v67, v2
	v_mov_b32_e32 v68, v2
	v_mov_b32_e32 v69, v2
	v_mov_b32_e32 v70, v2
	v_mov_b32_e32 v71, v2
	v_mov_b32_e32 v72, v2
	v_mov_b32_e32 v73, v2
	v_mov_b32_e32 v78, v2
	v_mov_b32_e32 v79, v2
	v_mov_b32_e32 v80, v2
	v_mov_b32_e32 v81, v2
	v_mov_b32_e32 v86, v2
	v_mov_b32_e32 v87, v2
	v_mov_b32_e32 v88, v2
	v_mov_b32_e32 v89, v2
	v_mov_b32_e32 v94, v2
	v_mov_b32_e32 v95, v2
	v_mov_b32_e32 v96, v2
	v_mov_b32_e32 v97, v2
	v_mov_b32_e32 v102, v2
	v_mov_b32_e32 v103, v2
	v_mov_b32_e32 v104, v2
	v_mov_b32_e32 v105, v2
	v_mov_b32_e32 v114, v2
	v_mov_b32_e32 v115, v2
	v_mov_b32_e32 v116, v2
	v_mov_b32_e32 v117, v2
	v_mov_b32_e32 v118, v2
	v_mov_b32_e32 v119, v2
	v_mov_b32_e32 v120, v2
	v_mov_b32_e32 v121, v2
	v_mov_b32_e32 v74, v2
	v_mov_b32_e32 v75, v2
	v_mov_b32_e32 v76, v2
	v_mov_b32_e32 v77, v2
	v_mov_b32_e32 v82, v2
	v_mov_b32_e32 v83, v2
	v_mov_b32_e32 v84, v2
	v_mov_b32_e32 v85, v2
	v_mov_b32_e32 v90, v2
	v_mov_b32_e32 v91, v2
	v_mov_b32_e32 v92, v2
	v_mov_b32_e32 v93, v2
	v_mov_b32_e32 v98, v2
	v_mov_b32_e32 v99, v2
	v_mov_b32_e32 v100, v2
	v_mov_b32_e32 v101, v2
	v_mov_b32_e32 v106, v2
	v_mov_b32_e32 v107, v2
	v_mov_b32_e32 v108, v2
	v_mov_b32_e32 v109, v2
	v_mov_b32_e32 v110, v2
	v_mov_b32_e32 v111, v2
	v_mov_b32_e32 v112, v2
	v_mov_b32_e32 v113, v2
	v_mov_b32_e32 v122, v2
	v_mov_b32_e32 v123, v2
	v_mov_b32_e32 v124, v2
	v_mov_b32_e32 v125, v2
	v_mov_b32_e32 v126, v2
	v_mov_b32_e32 v127, v2
	v_mov_b32_e32 v128, v2
	v_mov_b32_e32 v129, v2
	v_readlane_b32 s22, v253, 0
	s_nop 1
	s_cmp_eq_u32 s22, 0
	s_cbranch_scc1 .LBB0_412
	s_add_u32 s22, s12, 0xfffc0080
	s_addc_u32 s23, s13, -1
	s_add_i32 s53, 0, 0x10000
	s_cmp_eq_u32 s52, 12
	s_cselect_b32 s27, s25, s23
	s_cselect_b32 s26, s30, s22
	v_add_u32_e32 v134, s53, v178
	s_cselect_b32 s23, s37, s51
	s_cselect_b32 s22, s47, s50
	s_add_i32 s56, 0, 0x14000
	ds_read_b128 v[130:133], v134
	ds_read_b128 v[182:185], v134 offset:1024
	ds_read_b128 v[186:189], v134 offset:2048
	ds_read_b128 v[190:193], v134 offset:3072
	v_add_u32_e32 v134, s56, v178
	ds_read_b128 v[194:197], v134
	ds_read_b128 v[198:201], v134 offset:1024
	ds_read_b128 v[202:205], v134 offset:2048
	ds_read_b128 v[206:209], v134 offset:3072
	v_lshl_add_u64 v[160:161], s[12:13], 0, v[156:157]
	s_add_i32 m0, s31, 0xc000
	ds_read_b128 v[210:213], v180
	ds_read_b128 v[214:217], v180 offset:1024
	ds_read_b128 v[218:221], v180 offset:2048
	ds_read_b128 v[222:225], v180 offset:3072
	ds_read_b128 v[226:229], v180 offset:4096
	ds_read_b128 v[230:233], v180 offset:5120
	ds_read_b128 v[234:237], v180 offset:6144
	ds_read_b128 v[238:241], v180 offset:7168
	global_load_lds_dwordx4 v[160:161], off
	v_lshl_add_u64 v[160:161], s[12:13], 0, v[158:159]
	s_add_i32 m0, s31, 0xe000
	s_nop 0
	global_load_lds_dwordx4 v[160:161], off
	s_waitcnt vmcnt(16)
	s_waitcnt lgkmcnt(0)
	s_barrier
	s_setprio 1
	s_waitcnt lgkmcnt(0)
	v_mfma_f32_16x16x32_bf16 v[126:129], v[130:133], v[210:213], v[126:129]
	v_mfma_f32_16x16x32_bf16 v[122:125], v[186:189], v[210:213], v[122:125]
	v_mfma_f32_16x16x32_bf16 v[110:113], v[130:133], v[218:221], v[110:113]
	v_mfma_f32_16x16x32_bf16 v[106:109], v[186:189], v[218:221], v[106:109]
	v_mfma_f32_16x16x32_bf16 v[98:101], v[130:133], v[226:229], v[98:101]
	v_mfma_f32_16x16x32_bf16 v[90:93], v[186:189], v[226:229], v[90:93]
	v_mfma_f32_16x16x32_bf16 v[82:85], v[130:133], v[234:237], v[82:85]
	v_mfma_f32_16x16x32_bf16 v[74:77], v[186:189], v[234:237], v[74:77]
	v_mfma_f32_16x16x32_bf16 v[126:129], v[182:185], v[214:217], v[126:129]
	v_mfma_f32_16x16x32_bf16 v[122:125], v[190:193], v[214:217], v[122:125]
	v_mfma_f32_16x16x32_bf16 v[110:113], v[182:185], v[222:225], v[110:113]
	v_mfma_f32_16x16x32_bf16 v[106:109], v[190:193], v[222:225], v[106:109]
	v_mfma_f32_16x16x32_bf16 v[98:101], v[182:185], v[230:233], v[98:101]
	v_mfma_f32_16x16x32_bf16 v[90:93], v[190:193], v[230:233], v[90:93]
	v_mfma_f32_16x16x32_bf16 v[82:85], v[182:185], v[238:241], v[82:85]
	v_mfma_f32_16x16x32_bf16 v[74:77], v[190:193], v[238:241], v[74:77]
	s_setprio 0
	s_setprio 1
	v_mfma_f32_16x16x32_bf16 v[118:121], v[194:197], v[210:213], v[118:121]
	v_mfma_f32_16x16x32_bf16 v[114:117], v[202:205], v[210:213], v[114:117]
	v_mfma_f32_16x16x32_bf16 v[102:105], v[194:197], v[218:221], v[102:105]
	v_mfma_f32_16x16x32_bf16 v[94:97], v[202:205], v[218:221], v[94:97]
	v_mfma_f32_16x16x32_bf16 v[86:89], v[194:197], v[226:229], v[86:89]
	v_mfma_f32_16x16x32_bf16 v[78:81], v[202:205], v[226:229], v[78:81]
	v_mfma_f32_16x16x32_bf16 v[70:73], v[194:197], v[234:237], v[70:73]
	v_mfma_f32_16x16x32_bf16 v[66:69], v[202:205], v[234:237], v[66:69]
	v_mfma_f32_16x16x32_bf16 v[118:121], v[198:201], v[214:217], v[118:121]
	v_mfma_f32_16x16x32_bf16 v[114:117], v[206:209], v[214:217], v[114:117]
	v_mfma_f32_16x16x32_bf16 v[102:105], v[198:201], v[222:225], v[102:105]
	v_mfma_f32_16x16x32_bf16 v[94:97], v[206:209], v[222:225], v[94:97]
	s_setprio 2
	s_barrier
	v_mfma_f32_16x16x32_bf16 v[86:89], v[198:201], v[230:233], v[86:89]
	v_mfma_f32_16x16x32_bf16 v[78:81], v[206:209], v[230:233], v[78:81]
	v_mfma_f32_16x16x32_bf16 v[70:73], v[198:201], v[238:241], v[70:73]
	v_mfma_f32_16x16x32_bf16 v[66:69], v[206:209], v[238:241], v[66:69]
	s_setprio 0
	s_add_i32 s53, s53, s20
	v_lshl_add_u64 v[160:161], s[22:23], 0, v[148:149]
	s_mov_b32 m0, s53
	ds_read_b128 v[210:213], v180 offset:16384
	ds_read_b128 v[214:217], v180 offset:17408
	ds_read_b128 v[218:221], v180 offset:18432
	ds_read_b128 v[222:225], v180 offset:19456
	ds_read_b128 v[226:229], v180 offset:20480
	ds_read_b128 v[230:233], v180 offset:21504
	ds_read_b128 v[234:237], v180 offset:22528
	ds_read_b128 v[238:241], v180 offset:23552
	global_load_lds_dwordx4 v[160:161], off
	s_add_i32 m0, s53, 0x2000
	s_add_u32 s64, s22, 0x40000
	v_lshl_add_u64 v[164:165], s[22:23], 0, v[144:145]
	s_addc_u32 s65, s23, 0
	s_add_i32 s53, s56, s20
	global_load_lds_dwordx4 v[164:165], off
	v_lshl_add_u64 v[242:243], s[64:65], 0, v[148:149]
	s_mov_b32 m0, s53
	v_lshl_add_u64 v[244:245], s[26:27], 0, v[146:147]
	global_load_lds_dwordx4 v[242:243], off
	v_lshl_add_u64 v[242:243], s[64:65], 0, v[144:145]
	s_add_i32 m0, s53, 0x2000
	s_nop 0
	global_load_lds_dwordx4 v[242:243], off
	v_lshl_add_u64 v[242:243], s[26:27], 0, v[150:151]
	s_mov_b32 m0, s31
	s_nop 0
	global_load_lds_dwordx4 v[242:243], off
	s_mov_b32 m0, s35
	s_nop 0
	global_load_lds_dwordx4 v[244:245], off
	s_waitcnt vmcnt(16)
	s_waitcnt lgkmcnt(0)
	s_barrier
	s_setprio 1
	s_waitcnt lgkmcnt(0)
	v_mfma_f32_16x16x32_bf16 v[62:65], v[130:133], v[210:213], v[62:65]
	v_mfma_f32_16x16x32_bf16 v[58:61], v[186:189], v[210:213], v[58:61]
	v_mfma_f32_16x16x32_bf16 v[50:53], v[130:133], v[218:221], v[50:53]
	v_mfma_f32_16x16x32_bf16 v[42:45], v[186:189], v[218:221], v[42:45]
	v_mfma_f32_16x16x32_bf16 v[34:37], v[130:133], v[226:229], v[34:37]
	v_mfma_f32_16x16x32_bf16 v[26:29], v[186:189], v[226:229], v[26:29]
	v_mfma_f32_16x16x32_bf16 v[18:21], v[130:133], v[234:237], v[18:21]
	v_mfma_f32_16x16x32_bf16 v[10:13], v[186:189], v[234:237], v[10:13]
	v_mfma_f32_16x16x32_bf16 v[62:65], v[182:185], v[214:217], v[62:65]
	v_mfma_f32_16x16x32_bf16 v[58:61], v[190:193], v[214:217], v[58:61]
	v_mfma_f32_16x16x32_bf16 v[50:53], v[182:185], v[222:225], v[50:53]
	v_mfma_f32_16x16x32_bf16 v[42:45], v[190:193], v[222:225], v[42:45]
	v_mfma_f32_16x16x32_bf16 v[34:37], v[182:185], v[230:233], v[34:37]
	v_mfma_f32_16x16x32_bf16 v[26:29], v[190:193], v[230:233], v[26:29]
	v_mfma_f32_16x16x32_bf16 v[18:21], v[182:185], v[238:241], v[18:21]
	v_mfma_f32_16x16x32_bf16 v[10:13], v[190:193], v[238:241], v[10:13]
	s_setprio 0
	s_setprio 1
	v_mfma_f32_16x16x32_bf16 v[54:57], v[194:197], v[210:213], v[54:57]
	v_mfma_f32_16x16x32_bf16 v[46:49], v[202:205], v[210:213], v[46:49]
	v_mfma_f32_16x16x32_bf16 v[38:41], v[194:197], v[218:221], v[38:41]
	v_mfma_f32_16x16x32_bf16 v[30:33], v[202:205], v[218:221], v[30:33]
	v_mfma_f32_16x16x32_bf16 v[22:25], v[194:197], v[226:229], v[22:25]
	v_mfma_f32_16x16x32_bf16 v[14:17], v[202:205], v[226:229], v[14:17]
	v_mfma_f32_16x16x32_bf16 v[6:9], v[194:197], v[234:237], v[6:9]
	v_mfma_f32_16x16x32_bf16 v[2:5], v[202:205], v[234:237], v[2:5]
	v_mfma_f32_16x16x32_bf16 v[54:57], v[198:201], v[214:217], v[54:57]
	v_mfma_f32_16x16x32_bf16 v[46:49], v[206:209], v[214:217], v[46:49]
	v_mfma_f32_16x16x32_bf16 v[38:41], v[198:201], v[222:225], v[38:41]
	v_mfma_f32_16x16x32_bf16 v[30:33], v[206:209], v[222:225], v[30:33]
	s_setprio 2
	s_barrier
	v_mfma_f32_16x16x32_bf16 v[22:25], v[198:201], v[230:233], v[22:25]
	v_mfma_f32_16x16x32_bf16 v[14:17], v[206:209], v[230:233], v[14:17]
	v_mfma_f32_16x16x32_bf16 v[6:9], v[198:201], v[238:241], v[6:9]
	v_mfma_f32_16x16x32_bf16 v[2:5], v[206:209], v[238:241], v[2:5]
	s_setprio 0
	s_add_i32 s53, 0, 0x18000
	v_add_u32_e32 v134, s53, v178
	s_add_i32 s56, 0, 0x1c000
	ds_read_b128 v[130:133], v134
	ds_read_b128 v[182:185], v134 offset:1024
	ds_read_b128 v[186:189], v134 offset:2048
	ds_read_b128 v[190:193], v134 offset:3072
	v_add_u32_e32 v134, s56, v178
	ds_read_b128 v[194:197], v134
	ds_read_b128 v[198:201], v134 offset:1024
	ds_read_b128 v[202:205], v134 offset:2048
	ds_read_b128 v[206:209], v134 offset:3072
	s_add_u32 s26, s26, 0x40000
	s_addc_u32 s27, s27, 0
	s_mov_b32 m0, s38
	v_lshl_add_u64 v[246:247], s[26:27], 0, v[150:151]
	ds_read_b128 v[210:213], v180 offset:32768
	ds_read_b128 v[214:217], v180 offset:33792
	ds_read_b128 v[218:221], v180 offset:34816
	ds_read_b128 v[222:225], v180 offset:35840
	ds_read_b128 v[226:229], v180 offset:36864
	ds_read_b128 v[230:233], v180 offset:37888
	ds_read_b128 v[234:237], v180 offset:38912
	ds_read_b128 v[238:241], v180 offset:39936
	global_load_lds_dwordx4 v[246:247], off
	v_lshl_add_u64 v[246:247], s[26:27], 0, v[146:147]
	s_mov_b32 m0, s40
	s_nop 0
	global_load_lds_dwordx4 v[246:247], off
	s_waitcnt vmcnt(8)
	s_waitcnt lgkmcnt(0)
	s_barrier
	s_setprio 1
	s_waitcnt lgkmcnt(0)
	v_mfma_f32_16x16x32_bf16 v[126:129], v[130:133], v[210:213], v[126:129]
	v_mfma_f32_16x16x32_bf16 v[122:125], v[186:189], v[210:213], v[122:125]
	v_mfma_f32_16x16x32_bf16 v[110:113], v[130:133], v[218:221], v[110:113]
	v_mfma_f32_16x16x32_bf16 v[106:109], v[186:189], v[218:221], v[106:109]
	v_mfma_f32_16x16x32_bf16 v[98:101], v[130:133], v[226:229], v[98:101]
	v_mfma_f32_16x16x32_bf16 v[90:93], v[186:189], v[226:229], v[90:93]
	v_mfma_f32_16x16x32_bf16 v[82:85], v[130:133], v[234:237], v[82:85]
	v_mfma_f32_16x16x32_bf16 v[74:77], v[186:189], v[234:237], v[74:77]
	v_mfma_f32_16x16x32_bf16 v[126:129], v[182:185], v[214:217], v[126:129]
	v_mfma_f32_16x16x32_bf16 v[122:125], v[190:193], v[214:217], v[122:125]
	v_mfma_f32_16x16x32_bf16 v[110:113], v[182:185], v[222:225], v[110:113]
	v_mfma_f32_16x16x32_bf16 v[106:109], v[190:193], v[222:225], v[106:109]
	v_mfma_f32_16x16x32_bf16 v[98:101], v[182:185], v[230:233], v[98:101]
	v_mfma_f32_16x16x32_bf16 v[90:93], v[190:193], v[230:233], v[90:93]
	v_mfma_f32_16x16x32_bf16 v[82:85], v[182:185], v[238:241], v[82:85]
	v_mfma_f32_16x16x32_bf16 v[74:77], v[190:193], v[238:241], v[74:77]
	s_setprio 0
	s_setprio 1
	v_mfma_f32_16x16x32_bf16 v[118:121], v[194:197], v[210:213], v[118:121]
	v_mfma_f32_16x16x32_bf16 v[114:117], v[202:205], v[210:213], v[114:117]
	v_mfma_f32_16x16x32_bf16 v[102:105], v[194:197], v[218:221], v[102:105]
	v_mfma_f32_16x16x32_bf16 v[94:97], v[202:205], v[218:221], v[94:97]
	v_mfma_f32_16x16x32_bf16 v[86:89], v[194:197], v[226:229], v[86:89]
	v_mfma_f32_16x16x32_bf16 v[78:81], v[202:205], v[226:229], v[78:81]
	v_mfma_f32_16x16x32_bf16 v[70:73], v[194:197], v[234:237], v[70:73]
	v_mfma_f32_16x16x32_bf16 v[66:69], v[202:205], v[234:237], v[66:69]
	v_mfma_f32_16x16x32_bf16 v[118:121], v[198:201], v[214:217], v[118:121]
	v_mfma_f32_16x16x32_bf16 v[114:117], v[206:209], v[214:217], v[114:117]
	v_mfma_f32_16x16x32_bf16 v[102:105], v[198:201], v[222:225], v[102:105]
	v_mfma_f32_16x16x32_bf16 v[94:97], v[206:209], v[222:225], v[94:97]
	s_setprio 2
	s_barrier
	v_mfma_f32_16x16x32_bf16 v[86:89], v[198:201], v[230:233], v[86:89]
	v_mfma_f32_16x16x32_bf16 v[78:81], v[206:209], v[230:233], v[78:81]
	v_mfma_f32_16x16x32_bf16 v[70:73], v[198:201], v[238:241], v[70:73]
	v_mfma_f32_16x16x32_bf16 v[66:69], v[206:209], v[238:241], v[66:69]
	s_setprio 0
	s_add_i32 s26, s53, s20
	v_lshl_add_u64 v[160:161], v[160:161], 0, s[66:67]
	s_mov_b32 m0, s26
	ds_read_b128 v[210:213], v180 offset:49152
	ds_read_b128 v[214:217], v180 offset:50176
	ds_read_b128 v[218:221], v180 offset:51200
	ds_read_b128 v[222:225], v180 offset:52224
	ds_read_b128 v[226:229], v180 offset:53248
	ds_read_b128 v[230:233], v180 offset:54272
	ds_read_b128 v[234:237], v180 offset:55296
	ds_read_b128 v[238:241], v180 offset:56320
	global_load_lds_dwordx4 v[160:161], off
	s_add_i32 m0, s26, 0x2000
	s_add_u32 s22, s22, 0x40080
	v_lshl_add_u64 v[160:161], v[164:165], 0, s[66:67]
	s_addc_u32 s23, s23, 0
	s_add_i32 s26, s56, s20
	global_load_lds_dwordx4 v[160:161], off
	v_lshl_add_u64 v[160:161], s[22:23], 0, v[148:149]
	s_mov_b32 m0, s26
	s_nop 0
	global_load_lds_dwordx4 v[160:161], off
	v_lshl_add_u64 v[160:161], s[22:23], 0, v[144:145]
	s_add_i32 m0, s26, 0x2000
	s_nop 0
	global_load_lds_dwordx4 v[160:161], off
	v_lshl_add_u64 v[160:161], v[242:243], 0, s[66:67]
	s_mov_b32 m0, s41
	s_nop 0
	global_load_lds_dwordx4 v[160:161], off
	v_lshl_add_u64 v[160:161], v[244:245], 0, s[66:67]
	s_mov_b32 m0, s44
	s_nop 0
	global_load_lds_dwordx4 v[160:161], off
	s_waitcnt vmcnt(8)
	s_waitcnt lgkmcnt(0)
	s_barrier
	s_setprio 1
	s_waitcnt lgkmcnt(0)
	v_mfma_f32_16x16x32_bf16 v[62:65], v[130:133], v[210:213], v[62:65]
	v_mfma_f32_16x16x32_bf16 v[58:61], v[186:189], v[210:213], v[58:61]
	v_mfma_f32_16x16x32_bf16 v[50:53], v[130:133], v[218:221], v[50:53]
	v_mfma_f32_16x16x32_bf16 v[42:45], v[186:189], v[218:221], v[42:45]
	v_mfma_f32_16x16x32_bf16 v[34:37], v[130:133], v[226:229], v[34:37]
	v_mfma_f32_16x16x32_bf16 v[26:29], v[186:189], v[226:229], v[26:29]
	v_mfma_f32_16x16x32_bf16 v[18:21], v[130:133], v[234:237], v[18:21]
	v_mfma_f32_16x16x32_bf16 v[10:13], v[186:189], v[234:237], v[10:13]
	v_mfma_f32_16x16x32_bf16 v[62:65], v[182:185], v[214:217], v[62:65]
	v_mfma_f32_16x16x32_bf16 v[58:61], v[190:193], v[214:217], v[58:61]
	v_mfma_f32_16x16x32_bf16 v[50:53], v[182:185], v[222:225], v[50:53]
	v_mfma_f32_16x16x32_bf16 v[42:45], v[190:193], v[222:225], v[42:45]
	v_mfma_f32_16x16x32_bf16 v[34:37], v[182:185], v[230:233], v[34:37]
	v_mfma_f32_16x16x32_bf16 v[26:29], v[190:193], v[230:233], v[26:29]
	v_mfma_f32_16x16x32_bf16 v[18:21], v[182:185], v[238:241], v[18:21]
	v_mfma_f32_16x16x32_bf16 v[10:13], v[190:193], v[238:241], v[10:13]
	s_setprio 0
	s_setprio 1
	v_mfma_f32_16x16x32_bf16 v[54:57], v[194:197], v[210:213], v[54:57]
	v_mfma_f32_16x16x32_bf16 v[46:49], v[202:205], v[210:213], v[46:49]
	v_mfma_f32_16x16x32_bf16 v[38:41], v[194:197], v[218:221], v[38:41]
	v_mfma_f32_16x16x32_bf16 v[30:33], v[202:205], v[218:221], v[30:33]
	v_mfma_f32_16x16x32_bf16 v[22:25], v[194:197], v[226:229], v[22:25]
	v_mfma_f32_16x16x32_bf16 v[14:17], v[202:205], v[226:229], v[14:17]
	v_mfma_f32_16x16x32_bf16 v[6:9], v[194:197], v[234:237], v[6:9]
	v_mfma_f32_16x16x32_bf16 v[2:5], v[202:205], v[234:237], v[2:5]
	v_mfma_f32_16x16x32_bf16 v[54:57], v[198:201], v[214:217], v[54:57]
	v_mfma_f32_16x16x32_bf16 v[46:49], v[206:209], v[214:217], v[46:49]
	v_mfma_f32_16x16x32_bf16 v[38:41], v[198:201], v[222:225], v[38:41]
	v_mfma_f32_16x16x32_bf16 v[30:33], v[206:209], v[222:225], v[30:33]
	s_setprio 2
	s_barrier
	v_mfma_f32_16x16x32_bf16 v[22:25], v[198:201], v[230:233], v[22:25]
	v_mfma_f32_16x16x32_bf16 v[14:17], v[206:209], v[230:233], v[14:17]
	v_mfma_f32_16x16x32_bf16 v[6:9], v[198:201], v[238:241], v[6:9]
	v_mfma_f32_16x16x32_bf16 v[2:5], v[206:209], v[238:241], v[2:5]
	s_setprio 0
	s_add_i32 s52, s52, 2
	s_add_u32 s12, s12, 0x100
	s_addc_u32 s13, s13, 0
	s_add_u32 s50, s50, 0x100
	s_addc_u32 s51, s51, 0
	s_cmp_gt_u32 s52, 13
